# C1 + FFN2 walks its row-panel groups in reverse order inside each XCD (starts on the hidden panels FFN1 wrote last: Infinity-Cache reuse)
# baseline (speedup 1.0000x reference)
; #define PG8_STAGE(bufoff, gbase, voff) do { _Pragma("unroll") for (int _i = 0; _i < 2; ++_i) \
;         __builtin_amdgcn_global_load_lds((const unsigned*)((const char*)(gbase) + (voff)[_i]), (PG8_LAS unsigned*)(lds + (bufoff) + ldsw + _i * 8192), 16, 0, 0); } while (0)
; #define PG8_BAR __builtin_amdgcn_s_barrier()
;     __host__ __device__ bool next(int i, Unit& u) const {
;         const long L = (long)i * G + c; if (L >= nwg) return false;
;         int wgid = (int)L; { const int q = nwg / NXCD, r = nwg % NXCD, xcd = wgid % NXCD, off = wgid / NXCD; wgid = (xcd < r ? xcd * (q + 1) : r * (q + 1) + (xcd - r) * q) + off; }
;         const int nig = wgm * nN, gid = wgid / nig, fm = gid * wgm, gsz = (nM - fm) < wgm ? (nM - fm) : wgm;
;         u.pm = fm + ((wgid % nig) % gsz); u.pn = (wgid % nig) / gsz; return true;
;     }
; template <class Epi, class Sched, bool ALIGN_EPI = false, bool SP2 = false, bool ABLK = false, bool BBLK = false>
; __device__ __forceinline__ void gemm_phase(PG8_LAS unsigned char* lds, const Gemm g, const Sched& S, const Epi& E) {
;     ...
;     const char* cA = (const char*)g.A + (size_t)cur.pm * tstep; const char* cB = (const char*)g.Bt + (size_t)cur.pn * tstep;
;     S.a_ready(cur);
;     if constexpr (SP2) {
;         PG8_STAGE(PG8_SB(0, 0), cB, voffB); PG8_STAGE(PG8_SB(0, 1), cB + hstepB, voffB); PG8_STAGE(PG8_SA(0, 0), cA, voffA); PG8_STAGE(PG8_SA(0, 1), cA + hstepA, voffA);
;         if (wr == 1) PG8_BAR;
.LBB0_423:
	v_bfe_i32 v5, v10, 27, 1
	v_lshlrev_b32_e32 v3, 4, v10
	v_lshrrev_b32_e32 v5, 22, v5
	v_add_u32_e32 v5, v3, v5
	v_and_b32_e32 v5, 0xfffffc00, v5
	v_sub_u32_e32 v5, v3, v5
	v_lshrrev_b32_e32 v6, 4, v5
	v_bitop3_b32 v6, v6, v5, 32 bitop3:0x6c
	v_ashrrev_i32_e32 v5, 31, v5
	v_lshrrev_b32_e32 v5, 26, v5
	v_ashrrev_i32_e32 v4, 31, v10
	v_add_u32_e32 v5, v6, v5
	v_lshrrev_b32_e32 v4, 26, v4
	v_ashrrev_i32_e32 v5, 6, v5
	v_add_u32_e32 v4, v10, v4
	v_mul_i32_i24_e32 v9, 64, v5
	v_ashrrev_i32_e32 v4, 6, v4
	v_sub_u32_e32 v6, v6, v9
	v_lshlrev_b32_e32 v7, 3, v4
	v_lshlrev_b32_e32 v8, 5, v4
	v_ashrrev_i16_sdwa v6, v1, sext(v6) dst_sel:DWORD dst_unused:UNUSED_PAD src0_sel:DWORD src1_sel:BYTE_0
	v_and_b32_e32 v7, -16, v7
	v_and_b32_e32 v8, 32, v8
	v_bfe_i32 v6, v6, 0, 16
	v_add_u32_e32 v7, v5, v7
	v_and_b32_e32 v12, 3, v5
	s_mov_b32 s0, 0x1ffffe0
	v_add_lshl_u32 v8, v8, v6, 1
	v_add_u32_e32 v3, 0x2000, v3
	v_lshlrev_b32_e32 v9, 1, v7
	v_lshrrev_b32_e32 v11, 2, v7
	v_and_or_b32 v12, v7, s0, v12
	v_lshl_add_u32 v136, v7, 7, v8
	v_ashrrev_i32_e32 v7, 31, v3
	v_lshrrev_b32_e32 v7, 22, v7
	v_and_b32_e32 v9, 24, v9
	v_and_b32_e32 v11, 4, v11
	v_add_u32_e32 v7, v3, v7
	v_or3_b32 v9, v12, v11, v9
	v_ashrrev_i32_e32 v7, 10, v7
	v_lshl_add_u32 v138, v9, 7, v8
	v_mul_i32_i24_e32 v8, 0x400, v7
	v_sub_u32_e32 v3, v3, v8
	v_lshrrev_b32_e32 v8, 4, v3
	v_bitop3_b32 v3, v8, v3, 32 bitop3:0x6c
	v_lshlrev_b32_e32 v8, 3, v7
	v_and_b32_e32 v9, -16, v8
	v_ashrrev_i32_e32 v8, 31, v3
	v_lshrrev_b32_e32 v8, 26, v8
	v_add_u32_e32 v11, v3, v8
	v_ashrrev_i32_e32 v8, 6, v11
	v_add_u32_e32 v12, v8, v9
	v_and_b32_e32 v14, 3, v8
	v_and_or_b32 v14, v12, s0, v14
	s_ashr_i32 s0, s2, 6
	v_readlane_b32 s6, v255, 43
	s_ashr_i32 s1, s2, 8
	s_lshl_b32 s24, s0, 10
	v_readlane_b32 s7, v255, 44
	s_and_b64 s[6:7], s[6:7], exec
	s_mov_b32 s5, 0x5900000
	s_cselect_b32 s5, 0x6f00000, s5
	s_add_u32 s25, s54, s5
	s_addc_u32 s26, s55, 0
	s_add_i32 s3, s3, s4
	s_ashr_i32 s4, s3, 31
	s_lshr_b32 s4, s4, 27
	s_add_i32 s4, s3, s4
	s_ashr_i32 s5, s4, 5
	s_and_b32 s4, s4, 0xffe0
	s_sub_i32 s4, s3, s4
	s_bfe_i32 s3, s4, 0x80000
	s_bfe_u32 s3, s3, 0x2000d
	s_add_i32 s6, s4, s3
	s_bfe_i32 s3, s6, 0x80000
	s_and_b32 s6, s6, 0xfc
	s_sub_i32 s4, s4, s6
	v_lshlrev_b32_e32 v9, 5, v7
	s_lshl_b32 s5, s5, 2
	s_sext_i32_i16 s7, s3
	s_sext_i32_i8 s4, s4
	v_and_b32_e32 v13, 32, v9
	v_and_b32_e32 v9, 0xc0, v11
	s_add_i32 s71, s5, s4
	s_xor_b32 s71, s71, 12
	s_ashr_i32 s4, s7, 2
	v_sub_u32_e32 v3, v3, v9
	s_lshr_b32 s3, s7, 2
	s_mul_hi_i32 s5, s4, 0x2c0000
	s_mul_i32 s4, s4, 0x2c0000
	v_ashrrev_i16_sdwa v3, v1, sext(v3) dst_sel:DWORD dst_unused:UNUSED_PAD src0_sel:DWORD src1_sel:BYTE_0
	s_add_u32 s16, s25, s4
	v_bfe_i32 v9, v3, 0, 16
	v_lshlrev_b32_e32 v3, 1, v12
	v_lshrrev_b32_e32 v11, 2, v12
	s_addc_u32 s17, s26, s5
	s_add_i32 s27, s24, 0
	v_and_b32_e32 v3, 24, v3
	v_and_b32_e32 v11, 4, v11
	s_add_i32 m0, s27, 0x10000
	v_or3_b32 v3, v14, v11, v3
	v_add_lshl_u32 v11, v13, v9, 1
	global_load_lds_dwordx4 v138, s[16:17]
	s_add_i32 m0, s27, 0x12000
	v_lshl_add_u32 v142, v3, 7, v11
	s_add_u32 s4, s16, 0x4000
	global_load_lds_dwordx4 v142, s[16:17]
	s_addc_u32 s5, s17, 0
	s_add_i32 m0, s27, 0x14000
	s_mul_i32 s8, s71, 0x2c0000
	global_load_lds_dwordx4 v138, s[4:5]
	s_add_i32 m0, s27, 0x16000
	s_mul_hi_i32 s6, s71, 0x2c0000
	s_add_u32 s10, s96, s8
	s_addc_u32 s11, s97, s6
	s_add_i32 s28, s27, 0x2000
	global_load_lds_dwordx4 v142, s[4:5]
	s_mov_b32 m0, s27
	s_add_u32 s4, s10, 0x4000
	v_lshl_add_u32 v140, v12, 7, v11
	global_load_lds_dwordx4 v136, s[10:11]
	s_mov_b32 m0, s28
	s_addc_u32 s5, s11, 0
	s_add_i32 s29, s27, 0x4000
	global_load_lds_dwordx4 v140, s[10:11]
	s_mov_b32 m0, s29
	s_add_i32 s30, s27, 0x6000
	global_load_lds_dwordx4 v136, s[4:5]
	s_mov_b32 m0, s30
	s_cmp_eq_u32 s1, 1
	global_load_lds_dwordx4 v140, s[4:5]
	v_readlane_b32 s4, v252, 21
	v_readlane_b32 s5, v252, 22
	s_load_dword s31, s[4:5], 0x0
	s_mov_b32 s57, s37
	s_cselect_b64 s[4:5], -1, 0
	s_cmp_lg_u32 s1, 1
	s_cbranch_scc1 .LBB0_425
	s_barrier

;     __host__ __device__ bool next(int i, Unit& u) const {
;         const long L = (long)i * G + c; if (L >= nwg) return false;
;         int wgid = (int)L; { const int q = nwg / NXCD, r = nwg % NXCD, xcd = wgid % NXCD, off = wgid / NXCD; wgid = (xcd < r ? xcd * (q + 1) : r * (q + 1) + (xcd - r) * q) + off; }
;         const int nig = wgm * nN, gid = wgid / nig, fm = gid * wgm, gsz = (nM - fm) < wgm ? (nM - fm) : wgm;
;         u.pm = fm + ((wgid % nig) % gsz); u.pn = (wgid % nig) / gsz; return true;
;     }
.LBB0_433:
	s_ashr_i32 s2, s8, 3
	s_add_i32 s2, s12, s2
	s_ashr_i32 s3, s2, 31
	s_lshr_b32 s3, s3, 27
	s_add_i32 s3, s2, s3
	s_ashr_i32 s8, s3, 5
	s_lshl_b32 s8, s8, 2
	s_sub_i32 s9, 0x80, s8
	s_min_i32 s9, s9, 4
	s_abs_i32 s12, s9
	v_cvt_f32_u32_e32 v4, s12
	s_sub_i32 s18, 0, s12
	s_andn2_b32 s3, s3, 31
	s_sub_i32 s2, s2, s3
	v_rcp_iflag_f32_e32 v4, v4
	s_abs_i32 s3, s2
	s_xor_b32 s13, s2, s9
	s_ashr_i32 s13, s13, 31
	v_mul_f32_e32 v4, 0x4f7ffffe, v4
	v_cvt_u32_f32_e32 v4, v4
	s_nop 0
	v_readfirstlane_b32 s19, v4
	s_mul_i32 s18, s18, s19
	s_mul_hi_u32 s18, s19, s18
	s_add_i32 s19, s19, s18
	s_mul_hi_u32 s18, s3, s19
	s_mul_i32 s19, s18, s12
	s_sub_i32 s3, s3, s19
	s_add_i32 s20, s18, 1
	s_sub_i32 s19, s3, s12
	s_cmp_ge_u32 s3, s12
	s_cselect_b32 s18, s20, s18
	s_cselect_b32 s3, s19, s3
	s_add_i32 s19, s18, 1
	s_cmp_ge_u32 s3, s12
	s_cselect_b32 s3, s19, s18
	s_xor_b32 s3, s3, s13
	s_sub_i32 s77, s3, s13
	s_mul_i32 s3, s77, s9
	s_sub_i32 s2, s2, s3
	s_add_i32 s12, s8, s2
	s_xor_b32 s12, s12, 12
